# v20 + all mixer-phase stores write-through (sc0 sc1) so the per-workgroup L2 write-back before publishing has little to flush
# baseline (speedup 1.0000x reference)
.LBB0_548:
	v_readlane_b32 s14, v252, 1
	v_readlane_b32 s15, v252, 2
	v_lshlrev_b32_e32 v40, 2, v2
	s_mov_b64 s[12:13], -1
	s_and_b64 vcc, exec, s[14:15]
	s_cbranch_vccz .LBB0_550
	v_add_f32_e32 v2, v20, v21
	v_add_f32_e32 v8, v22, v23
	v_add_f32_e32 v2, v2, v8
	v_add_f32_e32 v8, v24, v25
	v_add_f32_e32 v9, v26, v27
	v_add_f32_e32 v2, 0, v2
	v_add_f32_e32 v8, v8, v9
	v_add_f32_e32 v2, v2, v8
	v_add_f32_e32 v8, v32, v33
	v_add_f32_e32 v9, v34, v35
	v_add_f32_e32 v8, v8, v9
	v_add_f32_e32 v2, v2, v8
	v_mov_b32_e32 v8, v37
	v_mov_b32_e32 v9, v38
	v_mov_b32_e32 v10, v36
	v_mov_b32_e32 v11, v39
	v_pk_add_f32 v[8:9], v[8:9], v[10:11]
	s_add_i32 s12, s0, s42
	v_add_f32_e32 v8, v8, v9
	v_and_b32_e32 v9, 64, v234
	v_add_f32_e32 v2, v2, v8
	v_xor_b32_e32 v8, 16, v234
	v_add_u32_e32 v9, 64, v9
	v_cmp_lt_i32_e32 vcc, v8, v9
	v_lshlrev_b32_e32 v56, 16, v188
	v_and_b32_e32 v57, 0xffff0000, v188
	v_cndmask_b32_e32 v8, v234, v8, vcc
	v_lshlrev_b32_e32 v16, 2, v8
	ds_bpermute_b32 v8, v16, v2
	v_readlane_b32 s14, v252, 27
	v_readlane_b32 s15, v252, 28
	s_waitcnt lgkmcnt(0)
	v_add_f32_e32 v2, v2, v8
	v_xor_b32_e32 v8, 32, v234
	v_cmp_lt_i32_e32 vcc, v8, v9
	v_add_u32_e32 v44, s14, v40
	v_ashrrev_i32_e32 v45, 31, v44
	v_cndmask_b32_e32 v8, v234, v8, vcc
	v_lshlrev_b32_e32 v17, 2, v8
	ds_bpermute_b32 v8, v17, v2
	s_waitcnt lgkmcnt(0)
	v_add_f32_e32 v18, v2, v8
	v_fmamk_f32 v149, v18, 0xbc800000, v21
	v_fmamk_f32 v148, v18, 0xbc800000, v20
	v_fmamk_f32 v155, v18, 0xbc800000, v23
	v_fmamk_f32 v154, v18, 0xbc800000, v22
	v_pk_mul_f32 v[8:9], v[154:155], v[154:155]
	v_pk_mul_f32 v[10:11], v[148:149], v[148:149]
	v_fmamk_f32 v153, v18, 0xbc800000, v25
	v_pk_mov_b32 v[12:13], v[10:11], v[8:9] op_sel:[1,0]
	v_mov_b32_e32 v11, v9
	v_fmamk_f32 v152, v18, 0xbc800000, v24
	v_fmamk_f32 v151, v18, 0xbc800000, v27
	v_fmamk_f32 v150, v18, 0xbc800000, v26
	v_pk_add_f32 v[8:9], v[12:13], v[10:11]
	v_pk_mul_f32 v[10:11], v[150:151], v[150:151]
	v_pk_mul_f32 v[12:13], v[152:153], v[152:153]
	v_fmamk_f32 v172, v18, 0xbc800000, v32
	v_pk_mov_b32 v[14:15], v[12:13], v[10:11] op_sel:[1,0]
	v_mov_b32_e32 v13, v11
	v_fmamk_f32 v168, v18, 0xbc800000, v34
	v_fmamk_f32 v173, v18, 0xbc800000, v33
	v_mul_f32_e32 v2, v172, v172
	v_pk_add_f32 v[10:11], v[14:15], v[12:13]
	v_fmamk_f32 v169, v18, 0xbc800000, v35
	v_pk_fma_f32 v[12:13], v[172:173], v[172:173], v[2:3] op_sel_hi:[1,1,0]
	v_mul_f32_e32 v2, v168, v168
	v_pk_add_f32 v[8:9], v[8:9], v[8:9] op_sel_hi:[0,1]
	v_pk_add_f32 v[10:11], v[10:11], v[10:11] op_sel_hi:[0,1]
	v_pk_fma_f32 v[14:15], v[168:169], v[168:169], v[2:3] op_sel_hi:[1,1,0]
	v_fmamk_f32 v171, v18, 0xbc800000, v39
	v_fmamk_f32 v170, v18, 0xbc800000, v38
	v_fmamk_f32 v175, v18, 0xbc800000, v37
	v_fmamk_f32 v174, v18, 0xbc800000, v36
	v_mul_f32_e32 v12, v174, v174
	v_mul_f32_e32 v14, v175, v175
	v_mul_f32_e32 v8, v170, v170
	v_mul_f32_e32 v10, v171, v171
	v_pk_add_f32 v[12:13], v[12:13], v[14:15]
	v_pk_add_f32 v[8:9], v[8:9], v[10:11]
	s_nop 0
	v_pk_add_f32 v[8:9], v[12:13], v[8:9]
	s_nop 0
	v_add_f32_e32 v2, v8, v9
	ds_bpermute_b32 v8, v16, v2
	s_waitcnt lgkmcnt(0)
	v_add_f32_e32 v2, v2, v8
	ds_bpermute_b32 v8, v17, v2
	v_lshrrev_b32_e32 v17, 2, v59
	v_or_b32_e32 v41, v40, v17
	s_waitcnt lgkmcnt(0)
	v_add_f32_e32 v2, v2, v8
	v_fmamk_f32 v2, v2, 0x3c800000, v156
	v_cmp_gt_f32_e32 vcc, s75, v2
	v_mul_f32_e32 v8, 0x4b800000, v2
	s_nop 0
	v_cndmask_b32_e32 v2, v2, v8, vcc
	v_rsq_f32_e32 v2, v2
	s_nop 0
	v_mul_f32_e32 v8, 0x45800000, v2
	v_cndmask_b32_e32 v16, v2, v8, vcc
	v_add_u32_e32 v84, s12, v59
	v_readlane_b32 s12, v252, 38
	v_subrev_u32_e32 v84, 63, v84
	v_lshlrev_b32_e32 v8, 3, v46
	v_and_b32_e32 v8, 24, v8
	v_add_u32_e32 v8, s55, v8
	v_mad_u32_u24 v61, v41, s89, v8
	v_lshl_add_u32 v9, v59, 2, s12
	ds_read_b32 v18, v9
	v_lshlrev_b32_e32 v10, 2, v40
	v_add_u32_e32 v19, 0x27600, v10
	v_add_u32_e32 v58, 0x27700, v10
	s_lshl_b32 s13, s0, 8
	s_add_i32 s13, s13, 0x20a00
	v_lshl_add_u32 v74, v46, 4, s13
	v_lshlrev_b32_e32 v56, 11, v84
	v_lshl_add_u32 v56, v44, 1, v56
	ds_read_b128 v[62:65], v19
	ds_read_b128 v[66:69], v58
	ds_read_b64_tr_b16 v[188:189], v61 offset:55296
	ds_read_b128 v[70:73], v74
	ds_read_b128 v[76:79], v19 offset:64
	ds_read_b128 v[184:187], v58 offset:64
	ds_read_b64_tr_b16 v[250:251], v61 offset:57600
	ds_read_b128 v[52:55], v74 offset:1024
	v_readlane_b32 s12, v252, 36
	v_readlane_b32 s13, v252, 37
	s_waitcnt lgkmcnt(4)
	v_pk_mul_f32 v[8:9], v[148:149], v[16:17] op_sel_hi:[1,0]
	v_pk_mul_f32 v[10:11], v[154:155], v[16:17] op_sel_hi:[1,0]
	v_pk_fma_f32 v[8:9], v[62:63], v[8:9], v[66:67]
	v_pk_fma_f32 v[10:11], v[64:65], v[10:11], v[68:69]
	v_lshlrev_b32_e32 v12, 16, v188
	v_and_b32_e32 v13, 0xffff0000, v188
	v_lshlrev_b32_e32 v14, 16, v189
	v_and_b32_e32 v15, 0xffff0000, v189
	v_pk_fma_f32 v[8:9], v[18:19], v[12:13], v[8:9] op_sel_hi:[0,1,1]
	v_pk_fma_f32 v[10:11], v[18:19], v[14:15], v[10:11] op_sel_hi:[0,1,1]
	v_pk_mul_f32 v[8:9], v[70:71], v[8:9]
	v_pk_mul_f32 v[10:11], v[72:73], v[10:11]
	v_cvt_pk_bf16_f32 v8, v8, v9
	v_cvt_pk_bf16_f32 v9, v10, v11
	global_store_dwordx2 v56, v[8:9], s[12:13] offset:1536 sc0 sc1
	ds_read_b128 v[62:65], v19 offset:128
	ds_read_b128 v[66:69], v58 offset:128
	ds_read_b64_tr_b16 v[188:189], v61 offset:59904
	ds_read_b128 v[70:73], v74 offset:2048
	s_waitcnt lgkmcnt(4)
	v_pk_mul_f32 v[8:9], v[152:153], v[16:17] op_sel_hi:[1,0]
	v_pk_mul_f32 v[10:11], v[150:151], v[16:17] op_sel_hi:[1,0]
	v_pk_fma_f32 v[8:9], v[76:77], v[8:9], v[184:185]
	v_pk_fma_f32 v[10:11], v[78:79], v[10:11], v[186:187]
	v_lshlrev_b32_e32 v12, 16, v250
	v_and_b32_e32 v13, 0xffff0000, v250
	v_lshlrev_b32_e32 v14, 16, v251
	v_and_b32_e32 v15, 0xffff0000, v251
	v_pk_fma_f32 v[8:9], v[18:19], v[12:13], v[8:9] op_sel_hi:[0,1,1]
	v_pk_fma_f32 v[10:11], v[18:19], v[14:15], v[10:11] op_sel_hi:[0,1,1]
	v_pk_mul_f32 v[8:9], v[52:53], v[8:9]
	v_pk_mul_f32 v[10:11], v[54:55], v[10:11]
	v_cvt_pk_bf16_f32 v8, v8, v9
	v_cvt_pk_bf16_f32 v9, v10, v11
	global_store_dwordx2 v56, v[8:9], s[12:13] offset:1568 sc0 sc1
	ds_read_b128 v[76:79], v19 offset:192
	ds_read_b128 v[184:187], v58 offset:192
	ds_read_b64_tr_b16 v[250:251], v61 offset:62208
	ds_read_b128 v[52:55], v74 offset:3072
	s_waitcnt lgkmcnt(4)
	v_pk_mul_f32 v[8:9], v[172:173], v[16:17] op_sel_hi:[1,0]
	v_pk_mul_f32 v[10:11], v[168:169], v[16:17] op_sel_hi:[1,0]
	v_pk_fma_f32 v[8:9], v[62:63], v[8:9], v[66:67]
	v_pk_fma_f32 v[10:11], v[64:65], v[10:11], v[68:69]
	v_lshlrev_b32_e32 v12, 16, v188
	v_and_b32_e32 v13, 0xffff0000, v188
	v_lshlrev_b32_e32 v14, 16, v189
	v_and_b32_e32 v15, 0xffff0000, v189
	v_pk_fma_f32 v[8:9], v[18:19], v[12:13], v[8:9] op_sel_hi:[0,1,1]
	v_pk_fma_f32 v[10:11], v[18:19], v[14:15], v[10:11] op_sel_hi:[0,1,1]
	v_pk_mul_f32 v[8:9], v[70:71], v[8:9]
	v_pk_mul_f32 v[10:11], v[72:73], v[10:11]
	v_cvt_pk_bf16_f32 v8, v8, v9
	v_cvt_pk_bf16_f32 v9, v10, v11
	global_store_dwordx2 v56, v[8:9], s[12:13] offset:1600 sc0 sc1
	s_waitcnt lgkmcnt(0)
	v_pk_mul_f32 v[8:9], v[174:175], v[16:17] op_sel_hi:[1,0]
	v_pk_mul_f32 v[10:11], v[170:171], v[16:17] op_sel_hi:[1,0]
	v_pk_fma_f32 v[8:9], v[76:77], v[8:9], v[184:185]
	v_pk_fma_f32 v[10:11], v[78:79], v[10:11], v[186:187]
	v_lshlrev_b32_e32 v12, 16, v250
	v_and_b32_e32 v13, 0xffff0000, v250
	v_lshlrev_b32_e32 v14, 16, v251
	v_and_b32_e32 v15, 0xffff0000, v251
	v_pk_fma_f32 v[8:9], v[18:19], v[12:13], v[8:9] op_sel_hi:[0,1,1]
	v_pk_fma_f32 v[10:11], v[18:19], v[14:15], v[10:11] op_sel_hi:[0,1,1]
	v_pk_mul_f32 v[8:9], v[52:53], v[8:9]
	v_pk_mul_f32 v[10:11], v[54:55], v[10:11]
	v_cvt_pk_bf16_f32 v8, v8, v9
	v_cvt_pk_bf16_f32 v9, v10, v11
	global_store_dwordx2 v56, v[8:9], s[12:13] offset:1632 sc0 sc1
	s_mov_b64 s[12:13], 0

.LBB0_553:
	v_readlane_b32 s12, v253, 4
	v_add_u32_e32 v9, 0x900, v47
	v_or_b32_e32 v8, s0, v59
	v_add_u32_e32 v10, s12, v2
	v_add_u32_e32 v11, v10, v9
	ds_read_b64 v[12:13], v11
	v_add3_u32 v11, s12, v9, v2
	ds_read_b64 v[14:15], v11 offset:32
	v_lshl_add_u32 v8, v8, 7, v60
	v_ashrrev_i32_e32 v9, 31, v8
	v_lshl_add_u64 v[8:9], s[38:39], 0, v[8:9]
	s_waitcnt lgkmcnt(0)
	v_mfma_f32_16x16x32_bf16 v[56:59], v[12:15], v[108:111], v[80:83]
	v_add_co_u32_e32 v14, vcc, 0x2000, v8
	v_cvt_pk_bf16_f32 v12, v20, v21
	v_cvt_pk_bf16_f32 v13, v22, v23
	v_addc_co_u32_e32 v15, vcc, 0, v9, vcc
	global_store_dwordx2 v[8:9], v[12:13], off sc0 sc1
	v_cvt_pk_bf16_f32 v12, v52, v53
	v_cvt_pk_bf16_f32 v13, v54, v55
	s_and_b64 vcc, exec, s[10:11]
	global_store_dwordx2 v[14:15], v[12:13], off sc0 sc1
	s_cbranch_vccnz .LBB0_555
	ds_read2_b64 v[12:15], v11 offset0:8 offset1:12
	s_waitcnt lgkmcnt(0)
	v_mfma_f32_16x16x32_bf16 v[56:59], v[12:15], v[112:115], v[56:59]
.LBB0_555:
	v_add_u32_e32 v14, 0x1200, v47
	v_readlane_b32 s12, v253, 4
	v_add_u32_e32 v12, v10, v14
	ds_read_b64 v[12:13], v12
	v_add3_u32 v16, s12, v14, v2
	ds_read_b64 v[14:15], v16 offset:32
	v_add_co_u32_e32 v40, vcc, 0x2000, v8
	s_nop 0
	v_mov_b32_e32 v11, v59
	v_cvt_pk_bf16_f32 v18, v24, v25
	v_cvt_pk_bf16_f32 v19, v26, v27
	s_waitcnt lgkmcnt(0)
	v_mfma_f32_16x16x32_bf16 v[12:15], v[12:15], v[108:111], v[28:31]
	v_addc_co_u32_e32 v41, vcc, 0, v9, vcc
	global_store_dwordx2 v[8:9], v[18:19], off offset:32 sc0 sc1
	v_cvt_pk_bf16_f32 v18, v56, v57
	v_cvt_pk_bf16_f32 v19, v58, v11
	s_and_b64 vcc, exec, s[10:11]
	global_store_dwordx2 v[40:41], v[18:19], off offset:32 sc0 sc1
	s_cbranch_vccnz .LBB0_557
	ds_read2_b64 v[16:19], v16 offset0:8 offset1:12
	s_waitcnt lgkmcnt(0)
	v_mfma_f32_16x16x32_bf16 v[12:15], v[16:19], v[112:115], v[12:15]
.LBB0_557:
	v_add_u32_e32 v40, 0x1b00, v47
	v_cvt_pk_bf16_f32 v16, v32, v33
	v_cvt_pk_bf16_f32 v17, v34, v35
	v_add_co_u32_e32 v18, vcc, 0x2000, v8
	v_readlane_b32 s12, v253, 4
	global_store_dwordx2 v[8:9], v[16:17], off offset:64 sc0 sc1
	s_nop 1
	v_cvt_pk_bf16_f32 v16, v12, v13
	v_cvt_pk_bf16_f32 v17, v14, v15
	v_addc_co_u32_e32 v19, vcc, 0, v9, vcc
	v_add_u32_e32 v10, v10, v40
	v_add3_u32 v2, s12, v40, v2
	global_store_dwordx2 v[18:19], v[16:17], off offset:64 sc0 sc1
	ds_read_b64 v[16:17], v10
	ds_read_b64 v[18:19], v2 offset:32
	s_waitcnt lgkmcnt(0)
	v_mfma_f32_16x16x32_bf16 v[16:19], v[16:19], v[108:111], v[48:51]
	s_and_b64 vcc, exec, s[10:11]
	s_cbranch_vccnz .LBB0_559
	ds_read2_b64 v[40:43], v2 offset0:8 offset1:12
	s_waitcnt lgkmcnt(0)
	v_mfma_f32_16x16x32_bf16 v[16:19], v[40:43], v[112:115], v[16:19]
.LBB0_559:
	v_cvt_pk_bf16_f32 v40, v36, v37
	v_cvt_pk_bf16_f32 v41, v38, v39
	global_store_dwordx2 v[8:9], v[40:41], off offset:96 sc0 sc1
	v_add_co_u32_e32 v8, vcc, 0x2000, v8
	s_nop 3
	v_cvt_pk_bf16_f32 v40, v16, v17
	v_addc_co_u32_e32 v9, vcc, 0, v9, vcc
	v_cvt_pk_bf16_f32 v41, v18, v19
	v_cmp_gt_u32_e32 vcc, 16, v46
	global_store_dwordx2 v[8:9], v[40:41], off offset:96 sc0 sc1
	s_and_saveexec_b64 s[10:11], vcc
	s_cbranch_execz .LBB0_561
	v_or_b32_e32 v2, s0, v46
	v_lshl_add_u32 v8, v2, 2, 0
	v_add_u32_e32 v10, 0x18500, v8
	v_lshl_add_u64 v[8:9], v[2:3], 2, s[38:39]
	ds_read_b32 v2, v10
	v_add_co_u32_e32 v8, vcc, 0x4000, v8
	s_nop 1
	v_addc_co_u32_e32 v9, vcc, 0, v9, vcc
	s_waitcnt lgkmcnt(0)
	global_store_dword v[8:9], v2, off sc0 sc1

.LBB0_573:
	s_and_b64 s[2:3], s[40:41], s[28:29]
	v_readlane_b32 s54, v253, 56
	v_readlane_b32 s44, v253, 45
	s_add_i32 s92, s38, 64
	s_and_b64 vcc, exec, s[2:3]
	v_readlane_b32 s96, v253, 8
	v_readlane_b32 s97, v253, 9
	v_readlane_b32 s55, v253, 57
	v_readlane_b32 s45, v253, 46
	v_readlane_b32 s43, v253, 58
	v_readlane_b32 s46, v252, 22
	v_readlane_b32 s47, v252, 21
	s_cbranch_vccz .LBB0_575
	s_lshl_b64 s[2:3], s[92:93], 13
	s_add_u32 s2, s72, s2
	s_addc_u32 s3, s73, s3
	s_lshl_b32 s0, s0, 1
	v_ashrrev_i32_e32 v0, 2, v161
	s_add_u32 s2, s2, s0
	v_and_b32_e32 v0, -4, v0
	s_addc_u32 s3, s3, 0
	v_ashrrev_i32_e32 v1, 31, v0
	v_lshlrev_b32_e32 v2, 7, v161
	v_lshl_add_u64 v[0:1], v[0:1], 1, s[2:3]
	v_and_b32_e32 v2, 0x780, v2
	v_lshl_add_u64 v[0:1], v[0:1], 0, v[2:3]
	s_mov_b32 s0, 0xdbac000
	s_waitcnt vmcnt(0)
	v_add_co_u32_e32 v8, vcc, s0, v0
	v_cvt_pk_bf16_f32 v4, v148, v149
	v_cvt_pk_bf16_f32 v5, v154, v155
	s_mov_b64 s[2:3], 0xdbac000
	v_addc_co_u32_e32 v9, vcc, 0, v1, vcc
	v_lshl_add_u64 v[6:7], v[0:1], 0, s[2:3]
	global_store_dwordx2 v[8:9], v[4:5], off sc0 sc1
	v_cvt_pk_bf16_f32 v4, v152, v153
	v_cvt_pk_bf16_f32 v5, v150, v151
	v_add_co_u32_e32 v0, vcc, 0xdbad000, v0
	global_store_dwordx2 v[6:7], v[4:5], off offset:2048 sc0 sc1
	v_cvt_pk_bf16_f32 v4, v172, v173
	v_cvt_pk_bf16_f32 v5, v168, v169
	v_addc_co_u32_e32 v1, vcc, 0, v1, vcc
	global_store_dwordx2 v[0:1], v[4:5], off sc0 sc1
	v_cvt_pk_bf16_f32 v4, v174, v175
	v_cvt_pk_bf16_f32 v5, v170, v171
	global_store_dwordx2 v[0:1], v[4:5], off offset:2048 sc0 sc1

.LBB0_603:
	s_waitcnt lgkmcnt(0)
	ds_read2_b64 v[52:55], v225 offset1:4
	s_waitcnt lgkmcnt(0)
	v_lshlrev_b32_e32 v56, 16, v52
	v_and_b32_e32 v57, 0xffff0000, v52
	v_lshlrev_b32_e32 v52, 16, v53
	v_and_b32_e32 v53, 0xffff0000, v53
	v_pk_fma_f32 v[44:45], v[100:101], v[56:57], v[44:45]
	v_pk_fma_f32 v[46:47], v[100:101], v[52:53], v[46:47]
	v_cvt_pk_bf16_f32 v44, v44, v45
	v_cvt_pk_bf16_f32 v45, v46, v47
	v_lshl_add_u64 v[46:47], s[72:73], 0, v[66:67]
	global_store_dwordx2 v[46:47], v[44:45], off sc0 sc1
	v_lshlrev_b32_e32 v44, 16, v54
	v_and_b32_e32 v45, 0xffff0000, v54
	v_lshlrev_b32_e32 v46, 16, v55
	v_and_b32_e32 v47, 0xffff0000, v55
	v_pk_fma_f32 v[44:45], v[100:101], v[44:45], v[48:49]
	v_pk_fma_f32 v[46:47], v[100:101], v[46:47], v[50:51]
	v_cvt_pk_bf16_f32 v44, v44, v45
	v_cvt_pk_bf16_f32 v45, v46, v47
	v_lshl_add_u64 v[46:47], s[72:73], 0, v[68:69]
	global_store_dwordx2 v[46:47], v[44:45], off sc0 sc1
	ds_read2_b64 v[44:47], v225 offset0:8 offset1:12
	s_waitcnt lgkmcnt(0)
	v_lshlrev_b32_e32 v48, 16, v44
	v_and_b32_e32 v49, 0xffff0000, v44
	v_lshlrev_b32_e32 v44, 16, v45
	v_and_b32_e32 v45, 0xffff0000, v45
	v_pk_fma_f32 v[36:37], v[100:101], v[48:49], v[36:37]
	v_pk_fma_f32 v[38:39], v[100:101], v[44:45], v[38:39]
	v_cvt_pk_bf16_f32 v36, v36, v37
	v_cvt_pk_bf16_f32 v37, v38, v39
	v_lshl_add_u64 v[38:39], s[72:73], 0, v[70:71]
	global_store_dwordx2 v[38:39], v[36:37], off sc0 sc1
	v_lshlrev_b32_e32 v36, 16, v46
	v_and_b32_e32 v37, 0xffff0000, v46
	v_lshlrev_b32_e32 v38, 16, v47
	v_and_b32_e32 v39, 0xffff0000, v47
	v_pk_fma_f32 v[36:37], v[100:101], v[36:37], v[40:41]
	v_pk_fma_f32 v[38:39], v[100:101], v[38:39], v[42:43]
	v_cvt_pk_bf16_f32 v36, v36, v37
	v_cvt_pk_bf16_f32 v37, v38, v39
	v_lshl_add_u64 v[38:39], s[72:73], 0, v[72:73]
	global_store_dwordx2 v[38:39], v[36:37], off sc0 sc1
	s_and_saveexec_b64 s[56:57], s[28:29]
	s_cbranch_execz .LBB0_605
	ds_read_b32 v1, v174
	v_lshl_add_u64 v[36:37], s[72:73], 0, v[82:83]
	s_waitcnt lgkmcnt(0)
	v_add_f32_e32 v1, v136, v1
	v_mul_f32_e32 v1, 0x3fb8aa3b, v1
	v_exp_f32_e32 v1, v1
	global_store_dword v[36:37], v1, off sc0 sc1
.LBB0_605:
	s_or_b64 exec, exec, s[56:57]
	ds_read_b128 v[36:39], v194
	v_lshl_add_u64 v[40:41], s[72:73], 0, v[110:111]
	s_waitcnt lgkmcnt(0)
	global_store_dwordx4 v[40:41], v[36:39], off sc0 sc1
	ds_read_b128 v[36:39], v195
	v_lshl_add_u64 v[40:41], s[72:73], 0, v[112:113]
	s_waitcnt lgkmcnt(0)
	global_store_dwordx4 v[40:41], v[36:39], off sc0 sc1
.LBB0_606:
	s_nop 2
	ds_read_b128 v[38:41], v196 offset:34816
	v_mov_b32_e32 v1, s0
	ds_read_b32 v36, v1 offset:508
	v_add_u32_e32 v1, v154, v155
	ds_read_b128 v[42:45], v1 offset:62464
	ds_read_b128 v[46:49], v196 offset:34880
	s_waitcnt lgkmcnt(4)
	ds_read_b128 v[50:53], v1 offset:62528
	ds_read_b128 v[54:57], v1 offset:64768
	ds_read_b128 v[58:61], v1 offset:64832
	v_add_u32_e32 v1, v154, v169
	ds_read_b128 v[224:227], v1 offset:62464
	ds_read_b128 v[242:245], v1 offset:62528
	ds_read_b128 v[246:249], v1 offset:64768
	s_waitcnt lgkmcnt(8)
	v_pk_mul_f32 v[30:31], v[30:31], v[36:37] op_sel_hi:[1,0]
	v_pk_mul_f32 v[28:29], v[28:29], v[36:37] op_sel_hi:[1,0]
	v_pk_mul_f32 v[26:27], v[26:27], v[36:37] op_sel_hi:[1,0]
	v_pk_mul_f32 v[24:25], v[24:25], v[36:37] op_sel_hi:[1,0]
	v_pk_mul_f32 v[22:23], v[22:23], v[36:37] op_sel_hi:[1,0]
	v_pk_mul_f32 v[20:21], v[20:21], v[36:37] op_sel_hi:[1,0]
	v_pk_mul_f32 v[6:7], v[6:7], v[36:37] op_sel_hi:[1,0]
	v_pk_mul_f32 v[4:5], v[4:5], v[36:37] op_sel_hi:[1,0]
	s_waitcnt lgkmcnt(7)
	v_mfma_f32_16x16x32_bf16 v[28:31], v[38:41], v[42:45], v[28:31]
	v_mul_f32_e64 v34, v34, v36
	v_mul_f32_e64 v35, v35, v36
	v_pk_mul_f32 v[32:33], v[32:33], v[36:37] op_sel_hi:[1,0]
	v_pk_mul_f32 v[18:19], v[18:19], v[36:37] op_sel_hi:[1,0]
	s_waitcnt lgkmcnt(4)
	v_mfma_f32_16x16x32_bf16 v[24:27], v[38:41], v[54:57], v[24:27]
	v_mul_f32_e64 v16, v16, v36
	v_mul_f32_e64 v17, v17, v36
	v_pk_mul_f32 v[14:15], v[14:15], v[36:37] op_sel_hi:[1,0]
	v_pk_mul_f32 v[12:13], v[12:13], v[36:37] op_sel_hi:[1,0]
	s_waitcnt lgkmcnt(2)
	v_mfma_f32_16x16x32_bf16 v[20:23], v[38:41], v[224:227], v[20:23]
	v_mul_f32_e64 v10, v10, v36
	v_mul_f32_e64 v11, v11, v36
	v_pk_mul_f32 v[8:9], v[8:9], v[36:37] op_sel_hi:[1,0]
	s_andn2_b64 vcc, exec, s[76:77]
	s_waitcnt lgkmcnt(0)
	v_mfma_f32_16x16x32_bf16 v[4:7], v[38:41], v[246:249], v[4:7]
	ds_read_b128 v[38:41], v1 offset:64832
	v_mfma_f32_16x16x32_bf16 v[28:31], v[46:49], v[50:53], v[28:31]
	v_mfma_f32_16x16x32_bf16 v[24:27], v[46:49], v[58:61], v[24:27]
	v_mfma_f32_16x16x32_bf16 v[20:23], v[46:49], v[242:245], v[20:23]
	s_waitcnt lgkmcnt(0)
	v_mfma_f32_16x16x32_bf16 v[4:7], v[46:49], v[38:41], v[4:7]
	ds_read_b128 v[46:49], v196 offset:37120
	s_waitcnt lgkmcnt(0)
	v_mfma_f32_16x16x32_bf16 v[32:35], v[46:49], v[42:45], v[32:35]
	ds_read_b128 v[42:45], v196 offset:37184
	s_waitcnt lgkmcnt(0)
	s_barrier
	v_mfma_f32_16x16x32_bf16 v[16:19], v[46:49], v[54:57], v[16:19]
	v_mfma_f32_16x16x32_bf16 v[12:15], v[46:49], v[224:227], v[12:15]
	v_mfma_f32_16x16x32_bf16 v[8:11], v[46:49], v[246:249], v[8:11]
	v_mfma_f32_16x16x32_bf16 v[32:35], v[42:45], v[50:53], v[32:35]
	v_mfma_f32_16x16x32_bf16 v[16:19], v[42:45], v[58:61], v[16:19]
	v_mfma_f32_16x16x32_bf16 v[12:15], v[42:45], v[242:245], v[12:15]
	v_mfma_f32_16x16x32_bf16 v[8:11], v[42:45], v[38:41], v[8:11]
	s_cbranch_vccnz .LBB0_583
	global_load_dwordx4 v[40:43], v[64:65], off
	global_load_dwordx4 v[52:55], v[64:65], off offset:64
	global_load_dwordx4 v[56:59], v[64:65], off offset:128
	global_load_dwordx4 v[224:227], v[64:65], off offset:192
	ds_read2st64_b32 v[36:37], v153 offset1:1
	s_waitcnt lgkmcnt(0)
	v_add_f32_e32 v1, v36, v37
	v_fmamk_f32 v1, v1, 0x3c000000, v158
	v_cmp_gt_f32_e32 vcc, s75, v1
	v_mul_f32_e32 v36, 0x4b800000, v1
	s_nop 0
	v_cndmask_b32_e32 v1, v1, v36, vcc
	v_rsq_f32_e32 v1, v1
	s_nop 0
	v_mul_f32_e32 v36, 0x45800000, v1
	v_cndmask_b32_e32 v38, v1, v36, vcc
	v_lshl_add_u64 v[36:37], s[72:73], 0, v[76:77]
	v_pk_mul_f32 v[44:45], v[118:119], v[38:39] op_sel_hi:[1,0]
	v_pk_mul_f32 v[242:243], v[120:121], v[38:39] op_sel_hi:[1,0]
	s_waitcnt vmcnt(0)
	v_pk_mul_f32 v[40:41], v[40:41], v[44:45]
	v_pk_mul_f32 v[42:43], v[42:43], v[242:243]
	v_cvt_pk_bf16_f32 v40, v40, v41
	v_cvt_pk_bf16_f32 v41, v42, v43
	global_store_dwordx2 v[36:37], v[40:41], off offset:-64 sc0 sc1
	v_pk_mul_f32 v[44:45], v[122:123], v[38:39] op_sel_hi:[1,0]
	v_pk_mul_f32 v[242:243], v[124:125], v[38:39] op_sel_hi:[1,0]
	v_pk_mul_f32 v[52:53], v[52:53], v[44:45]
	v_pk_mul_f32 v[54:55], v[54:55], v[242:243]
	v_cvt_pk_bf16_f32 v52, v52, v53
	v_cvt_pk_bf16_f32 v53, v54, v55
	global_store_dwordx2 v[36:37], v[52:53], off offset:-32 sc0 sc1
	v_pk_mul_f32 v[44:45], v[126:127], v[38:39] op_sel_hi:[1,0]
	v_pk_mul_f32 v[242:243], v[128:129], v[38:39] op_sel_hi:[1,0]
	v_pk_mul_f32 v[56:57], v[56:57], v[44:45]
	v_pk_mul_f32 v[58:59], v[58:59], v[242:243]
	v_cvt_pk_bf16_f32 v56, v56, v57
	v_cvt_pk_bf16_f32 v57, v58, v59
	global_store_dwordx2 v[36:37], v[56:57], off sc0 sc1
	v_pk_mul_f32 v[44:45], v[130:131], v[38:39] op_sel_hi:[1,0]
	v_pk_mul_f32 v[242:243], v[132:133], v[38:39] op_sel_hi:[1,0]
	v_pk_mul_f32 v[224:225], v[224:225], v[44:45]
	v_pk_mul_f32 v[226:227], v[226:227], v[242:243]
	v_cvt_pk_bf16_f32 v224, v224, v225
	v_cvt_pk_bf16_f32 v225, v226, v227
	global_store_dwordx2 v[36:37], v[224:225], off offset:32 sc0 sc1
	s_branch .LBB0_583

.LBB0_609:
	v_or_b32_e32 v1, s59, v145
	v_readlane_b32 s2, v252, 19
	v_cmp_eq_u32_e32 vcc, 0, v1
	v_readlane_b32 s3, v252, 20
	s_and_b64 s[4:5], s[2:3], vcc
	s_and_saveexec_b64 s[2:3], s[4:5]
	s_cbranch_execz .LBB0_611
	s_lshl_b32 s0, s56, 3
	s_add_u32 s0, s72, s0
	s_addc_u32 s6, s73, 0
	v_exp_f32_e32 v0, v0
	s_ashr_i32 s9, s8, 31
	s_lshl_b64 s[4:5], s[8:9], 2
	s_add_u32 s4, s0, s4
	s_addc_u32 s5, s6, s5
	v_mov_b32_e32 v1, 0xec80000
	global_store_dword v1, v0, s[4:5] sc0 sc1
.LBB0_611:
	s_or_b64 exec, exec, s[2:3]
	s_cmp_gt_i32 s53, 1
	s_cbranch_scc1 .LBB0_613
	s_and_b64 s[2:3], s[76:77], exec
	s_mov_b32 s0, 0x2d80000
	s_cselect_b32 s0, s0, 0x2e00000
	s_add_u32 s0, s46, s0
	s_addc_u32 s2, s47, 0
	s_lshl_b32 s3, s56, 15
	s_add_u32 s0, s0, s3
	s_addc_u32 s3, s2, 0
	s_lshl_b32 s2, s8, 14
	s_ashr_i32 s4, s2, 31
	s_add_u32 s2, s0, s2
	s_addc_u32 s3, s3, s4
	v_lshlrev_b32_e32 v2, 1, v2
	v_lshl_add_u64 v[0:1], s[2:3], 0, v[2:3]
	s_lshl_b32 s92, s59, 6
	v_lshl_add_u64 v[0:1], v[0:1], 0, s[92:93]
	v_lshlrev_b32_e32 v2, 8, v144
	v_cvt_pk_bf16_f32 v28, v28, v29
	v_cvt_pk_bf16_f32 v29, v30, v31
	v_lshl_add_u64 v[30:31], v[0:1], 0, v[2:3]
	v_cvt_pk_bf16_f32 v24, v24, v25
	v_cvt_pk_bf16_f32 v25, v26, v27
	v_or_b32_e32 v26, 0x1000, v2
	v_mov_b32_e32 v27, v3
	v_cvt_pk_bf16_f32 v20, v20, v21
	v_cvt_pk_bf16_f32 v21, v22, v23
	v_or_b32_e32 v22, 0x2000, v2
	v_or_b32_e32 v2, 0x3000, v2
	global_store_dwordx2 v[30:31], v[28:29], off sc0 sc1
	v_lshl_add_u64 v[28:29], v[0:1], 0, v[26:27]
	v_mov_b32_e32 v23, v3
	v_cvt_pk_bf16_f32 v4, v4, v5
	v_cvt_pk_bf16_f32 v5, v6, v7
	v_lshl_add_u64 v[6:7], v[0:1], 0, v[2:3]
	global_store_dwordx2 v[28:29], v[24:25], off sc0 sc1
	v_lshl_add_u64 v[24:25], v[0:1], 0, v[22:23]
	global_store_dwordx2 v[6:7], v[4:5], off sc0 sc1
	v_lshl_add_u64 v[0:1], v[0:1], 0, 32
	v_cvt_pk_bf16_f32 v4, v32, v33
	v_cvt_pk_bf16_f32 v5, v34, v35
	global_store_dwordx2 v[30:31], v[4:5], off offset:32 sc0 sc1
	v_cvt_pk_bf16_f32 v4, v16, v17
	v_cvt_pk_bf16_f32 v5, v18, v19
	v_lshl_add_u64 v[6:7], v[0:1], 0, v[26:27]
	global_store_dwordx2 v[6:7], v[4:5], off sc0 sc1
	v_cvt_pk_bf16_f32 v4, v12, v13
	v_cvt_pk_bf16_f32 v5, v14, v15
	v_lshl_add_u64 v[6:7], v[0:1], 0, v[22:23]
	global_store_dwordx2 v[6:7], v[4:5], off sc0 sc1
	v_cvt_pk_bf16_f32 v4, v8, v9
	v_cvt_pk_bf16_f32 v5, v10, v11
	v_lshl_add_u64 v[0:1], v[0:1], 0, v[2:3]
	global_store_dwordx2 v[24:25], v[20:21], off sc0 sc1
	global_store_dwordx2 v[0:1], v[4:5], off sc0 sc1

.LBB0_726:
	v_add_u32_e32 v11, 0x900, v53
	v_add_u32_e32 v60, s14, v52
	v_add_u32_e32 v0, v60, v11
	ds_read_b128 v[12:15], v0
	v_lshlrev_b32_e32 v2, 6, v54
	v_lshlrev_b32_e32 v0, 2, v10
	v_readlane_b32 s15, v252, 3
	v_ashrrev_i32_e32 v1, 31, v0
	s_add_u32 s16, s72, s77
	v_add_lshl_u32 v2, s15, v2, 1
	v_lshl_add_u64 v[0:1], v[0:1], 1, v[2:3]
	s_addc_u32 s17, s73, s82
	v_lshl_add_u64 v[0:1], s[16:17], 0, v[0:1]
	s_mov_b32 s15, 0xedc0000
	v_add_co_u32_e32 v8, vcc, s15, v0
	s_waitcnt lgkmcnt(0)
	v_mfma_f32_16x16x32_bf16 v[24:27], v[12:15], v[16:19], v[80:83]
	v_addc_co_u32_e32 v9, vcc, 0, v1, vcc
	v_add_co_u32_e32 v14, vcc, 0xedc2000, v0
	v_cvt_pk_bf16_f32 v12, v28, v29
	v_cvt_pk_bf16_f32 v13, v30, v31
	v_addc_co_u32_e32 v15, vcc, 0, v1, vcc
	global_store_dwordx2 v[8:9], v[12:13], off sc0 sc1
	v_cvt_pk_bf16_f32 v12, v20, v21
	v_cvt_pk_bf16_f32 v13, v22, v23
	s_and_b64 vcc, exec, s[12:13]
	global_store_dwordx2 v[14:15], v[12:13], off sc0 sc1
	s_cbranch_vccnz .LBB0_728
	v_add3_u32 v2, s14, v11, v52
	ds_read_b128 v[12:15], v2 offset:64
	s_waitcnt lgkmcnt(0)
	v_mfma_f32_16x16x32_bf16 v[24:27], v[12:15], v[48:51], v[24:27]
.LBB0_728:
	v_add_u32_e32 v2, 0x1200, v53
	v_add_u32_e32 v12, v60, v2
	ds_read_b128 v[12:15], v12
	v_cvt_pk_bf16_f32 v62, v32, v33
	v_cvt_pk_bf16_f32 v63, v34, v35
	global_store_dwordx2 v[8:9], v[62:63], off offset:32 sc0 sc1
	v_add_co_u32_e32 v62, vcc, 0xedc2000, v0
	s_nop 0
	v_mov_b32_e32 v11, v27
	v_addc_co_u32_e32 v63, vcc, 0, v1, vcc
	s_waitcnt lgkmcnt(0)
	v_mfma_f32_16x16x32_bf16 v[12:15], v[12:15], v[16:19], v[36:39]
	v_cvt_pk_bf16_f32 v8, v24, v25
	v_cvt_pk_bf16_f32 v9, v26, v11
	s_and_b64 vcc, exec, s[12:13]
	global_store_dwordx2 v[62:63], v[8:9], off offset:32 sc0 sc1
	s_cbranch_vccnz .LBB0_730
	v_add3_u32 v2, s14, v2, v52
	ds_read_b128 v[62:65], v2 offset:64
	s_waitcnt lgkmcnt(0)
	v_mfma_f32_16x16x32_bf16 v[12:15], v[62:65], v[48:51], v[12:15]
.LBB0_730:
	v_add_co_u32_e32 v62, vcc, 0xedc0000, v0
	v_cvt_pk_bf16_f32 v8, v40, v41
	v_cvt_pk_bf16_f32 v9, v42, v43
	v_addc_co_u32_e32 v63, vcc, 0, v1, vcc
	global_store_dwordx2 v[62:63], v[8:9], off offset:64 sc0 sc1
	v_add_co_u32_e32 v62, vcc, 0xedc2000, v0
	v_add_u32_e32 v2, 0x1b00, v53
	s_nop 0
	v_cvt_pk_bf16_f32 v8, v12, v13
	v_cvt_pk_bf16_f32 v9, v14, v15
	v_addc_co_u32_e32 v63, vcc, 0, v1, vcc
	global_store_dwordx2 v[62:63], v[8:9], off offset:64 sc0 sc1
	v_add_u32_e32 v8, v60, v2
	ds_read_b128 v[60:63], v8
	s_waitcnt lgkmcnt(0)
	v_mfma_f32_16x16x32_bf16 v[16:19], v[60:63], v[16:19], v[56:59]
	s_and_b64 vcc, exec, s[12:13]
	s_cbranch_vccnz .LBB0_732
	v_add3_u32 v2, s14, v2, v52
	ds_read_b128 v[60:63], v2 offset:64
	s_waitcnt lgkmcnt(0)
	v_mfma_f32_16x16x32_bf16 v[16:19], v[60:63], v[48:51], v[16:19]
.LBB0_732:
	v_add_co_u32_e32 v48, vcc, 0xedc0000, v0
	v_cvt_pk_bf16_f32 v8, v44, v45
	s_nop 0
	v_addc_co_u32_e32 v49, vcc, 0, v1, vcc
	v_cvt_pk_bf16_f32 v9, v46, v47
	v_add_co_u32_e32 v0, vcc, 0xedc2000, v0
	global_store_dwordx2 v[48:49], v[8:9], off offset:96 sc0 sc1
	s_nop 0
	v_cvt_pk_bf16_f32 v8, v16, v17
	v_cvt_pk_bf16_f32 v9, v18, v19
	v_addc_co_u32_e32 v1, vcc, 0, v1, vcc
	global_store_dwordx2 v[0:1], v[8:9], off offset:96 sc0 sc1
	s_branch .LBB0_735
.LBB0_733:
	s_and_b64 vcc, exec, s[14:15]
	s_cbranch_vccz .LBB0_735
	v_mul_f32_e32 v0, v29, v29
	v_mul_f32_e32 v1, v31, v31
	v_fmac_f32_e32 v0, v28, v28
	v_fmac_f32_e32 v1, v30, v30
	v_add_f32_e32 v0, v0, v1
	v_mul_f32_e32 v1, v33, v33
	v_mul_f32_e32 v2, v35, v35
	v_fmac_f32_e32 v1, v32, v32
	v_fmac_f32_e32 v2, v34, v34
	v_add_f32_e32 v1, v1, v2
	v_add_f32_e32 v0, v0, v1
	v_mul_f32_e32 v1, v41, v41
	v_mul_f32_e32 v2, v43, v43
	v_fmac_f32_e32 v1, v40, v40
	v_fmac_f32_e32 v2, v42, v42
	v_add_f32_e32 v1, v1, v2
	v_add_f32_e32 v2, v0, v1
	v_pk_mul_f32 v[0:1], v[46:47], v[46:47]
	v_pk_mul_f32 v[8:9], v[44:45], v[44:45]
	s_add_i32 s12, s55, s54
	v_pk_mov_b32 v[12:13], v[8:9], v[0:1] op_sel:[1,0]
	v_mov_b32_e32 v9, v1
	v_pk_add_f32 v[0:1], v[12:13], v[8:9]
	v_lshlrev_b32_e32 v8, 2, v10
	v_add_f32_e32 v0, v0, v1
	v_add_f32_e32 v0, v2, v0
	v_and_b32_e32 v2, 64, v234
	v_xor_b32_e32 v1, 16, v234
	v_add_u32_e32 v2, 64, v2
	v_cmp_lt_i32_e32 vcc, v1, v2
	v_ashrrev_i32_e32 v9, 31, v8
	v_add_u32_e32 v12, s53, v8
	v_cndmask_b32_e32 v1, v234, v1, vcc
	v_lshlrev_b32_e32 v1, 2, v1
	ds_bpermute_b32 v1, v1, v0
	v_ashrrev_i32_e32 v13, 31, v12
	v_lshlrev_b64 v[12:13], 1, v[12:13]
	s_waitcnt lgkmcnt(0)
	v_add_f32_e32 v0, v0, v1
	v_xor_b32_e32 v1, 32, v234
	v_cmp_lt_i32_e32 vcc, v1, v2
	v_add_u32_e32 v2, s12, v54
	v_readlane_b32 s12, v253, 50
	v_cndmask_b32_e32 v1, v234, v1, vcc
	v_lshlrev_b32_e32 v1, 2, v1
	ds_bpermute_b32 v1, v1, v0
	v_readlane_b32 s13, v253, 51
	s_waitcnt lgkmcnt(0)
	v_add_f32_e32 v0, v0, v1
	v_fmamk_f32 v0, v0, 0x3c800000, v158
	v_cmp_gt_f32_e32 vcc, s75, v0
	v_mul_f32_e32 v1, 0x4b800000, v0
	v_lshl_add_u64 v[14:15], v[8:9], 2, s[12:13]
	v_cndmask_b32_e32 v0, v0, v1, vcc
	v_mov_b64_e32 v[8:9], s[40:41]
	v_rsq_f32_e32 v0, v0
	v_mad_u64_u32 v[16:17], s[12:13], v2, s64, v[8:9]
	v_readlane_b32 s12, v253, 48
	v_lshlrev_b64 v[8:9], 11, v[2:3]
	v_readlane_b32 s13, v253, 49
	v_lshl_add_u64 v[20:21], v[16:17], 0, v[12:13]
	v_mul_f32_e32 v1, 0x45800000, v0
	v_lshl_add_u64 v[18:19], s[12:13], 0, v[8:9]
	s_mov_b64 s[12:13], 0x1a00
	v_lshl_add_u64 v[16:17], v[20:21], 0, s[12:13]
	s_movk_i32 s12, 0x1000
	v_cndmask_b32_e32 v0, v0, v1, vcc
	v_lshl_add_u64 v[12:13], v[18:19], 0, v[12:13]
	s_waitcnt vmcnt(0)
	v_mov_b64_e32 v[8:9], v[248:249]
	v_mov_b64_e32 v[10:11], v[250:251]
	v_mov_b64_e32 v[20:21], v[254:255]
	v_lshlrev_b32_e32 v22, 16, v20
	v_mul_f32_e32 v1, 0xbfb8aa3b, v22
	v_exp_f32_e32 v1, v1
	v_and_b32_e32 v23, 0xffff0000, v20
	v_lshlrev_b32_e32 v20, 16, v21
	v_and_b32_e32 v21, 0xffff0000, v21
	v_add_f32_e32 v1, 1.0, v1
	v_rcp_f32_e32 v24, v1
	v_pk_mul_f32 v[26:27], v[28:29], v[0:1] op_sel_hi:[1,0]
	v_mul_f32_e32 v1, 0xbfb8aa3b, v23
	v_exp_f32_e32 v1, v1
	v_pk_mul_f32 v[8:9], v[8:9], v[26:27]
	v_mov_b32_e32 v26, v82
	v_add_f32_e32 v1, 1.0, v1
	v_rcp_f32_e32 v25, v1
	v_mul_f32_e32 v1, 0xbfb8aa3b, v20
	v_exp_f32_e32 v1, v1
	v_pk_mul_f32 v[22:23], v[24:25], v[22:23]
	s_nop 0
	v_pk_mul_f32 v[8:9], v[22:23], v[8:9]
	v_add_f32_e32 v1, 1.0, v1
	v_rcp_f32_e32 v22, v1
	v_pk_mul_f32 v[24:25], v[30:31], v[0:1] op_sel_hi:[1,0]
	v_mul_f32_e32 v1, 0xbfb8aa3b, v21
	v_exp_f32_e32 v1, v1
	v_pk_mul_f32 v[10:11], v[10:11], v[24:25]
	v_cvt_pk_bf16_f32 v8, v8, v9
	v_add_f32_e32 v1, 1.0, v1
	v_rcp_f32_e32 v23, v1
	s_nop 0
	v_pk_mul_f32 v[20:21], v[22:23], v[20:21]
	s_nop 0
	v_pk_mul_f32 v[10:11], v[20:21], v[10:11]
	s_nop 0
	v_cvt_pk_bf16_f32 v9, v10, v11
	global_store_dwordx2 v[12:13], v[8:9], off offset:512 sc0 sc1
	v_mov_b64_e32 v[8:9], v[68:69]
	v_mov_b64_e32 v[10:11], v[70:71]
	v_mov_b64_e32 v[18:19], v[72:73]
	v_lshlrev_b32_e32 v20, 16, v18
	v_mul_f32_e32 v1, 0xbfb8aa3b, v20
	v_exp_f32_e32 v1, v1
	v_and_b32_e32 v21, 0xffff0000, v18
	v_lshlrev_b32_e32 v18, 16, v19
	v_and_b32_e32 v19, 0xffff0000, v19
	v_add_f32_e32 v1, 1.0, v1
	v_rcp_f32_e32 v22, v1
	v_pk_mul_f32 v[24:25], v[32:33], v[0:1] op_sel_hi:[1,0]
	v_mul_f32_e32 v1, 0xbfb8aa3b, v21
	v_exp_f32_e32 v1, v1
	v_pk_mul_f32 v[8:9], v[8:9], v[24:25]
	v_add_f32_e32 v1, 1.0, v1
	v_rcp_f32_e32 v23, v1
	v_mul_f32_e32 v1, 0xbfb8aa3b, v18
	v_exp_f32_e32 v1, v1
	v_pk_mul_f32 v[20:21], v[22:23], v[20:21]
	s_nop 0
	v_pk_mul_f32 v[8:9], v[8:9], v[20:21]
	v_add_f32_e32 v1, 1.0, v1
	v_rcp_f32_e32 v20, v1
	v_pk_mul_f32 v[22:23], v[34:35], v[0:1] op_sel_hi:[1,0]
	v_mul_f32_e32 v1, 0xbfb8aa3b, v19
	v_exp_f32_e32 v1, v1
	v_pk_mul_f32 v[10:11], v[10:11], v[22:23]
	v_cvt_pk_bf16_f32 v8, v8, v9
	v_add_f32_e32 v1, 1.0, v1
	v_rcp_f32_e32 v21, v1
	s_nop 0
	v_pk_mul_f32 v[18:19], v[20:21], v[18:19]
	s_nop 0
	v_pk_mul_f32 v[10:11], v[10:11], v[18:19]
	s_nop 0
	v_cvt_pk_bf16_f32 v9, v10, v11
	global_store_dwordx2 v[12:13], v[8:9], off offset:544 sc0 sc1
	v_mov_b64_e32 v[8:9], v[224:225]
	v_mov_b64_e32 v[10:11], v[226:227]
	v_mov_b64_e32 v[18:19], v[228:229]
	v_lshlrev_b32_e32 v20, 16, v18
	v_mul_f32_e32 v1, 0xbfb8aa3b, v20
	v_exp_f32_e32 v1, v1
	v_and_b32_e32 v21, 0xffff0000, v18
	v_lshlrev_b32_e32 v18, 16, v19
	v_and_b32_e32 v19, 0xffff0000, v19
	v_add_f32_e32 v1, 1.0, v1
	v_rcp_f32_e32 v22, v1
	v_pk_mul_f32 v[24:25], v[40:41], v[0:1] op_sel_hi:[1,0]
	v_mul_f32_e32 v1, 0xbfb8aa3b, v21
	v_exp_f32_e32 v1, v1
	v_pk_mul_f32 v[8:9], v[8:9], v[24:25]
	v_mov_b32_e32 v25, v81
	v_mov_b32_e32 v24, v80
	v_add_f32_e32 v1, 1.0, v1
	v_rcp_f32_e32 v23, v1
	v_mul_f32_e32 v1, 0xbfb8aa3b, v18
	v_exp_f32_e32 v1, v1
	v_pk_mul_f32 v[20:21], v[22:23], v[20:21]
	s_nop 0
	v_pk_mul_f32 v[8:9], v[8:9], v[20:21]
	v_add_f32_e32 v1, 1.0, v1
	v_rcp_f32_e32 v20, v1
	v_pk_mul_f32 v[22:23], v[42:43], v[0:1] op_sel_hi:[1,0]
	v_mul_f32_e32 v1, 0xbfb8aa3b, v19
	v_exp_f32_e32 v1, v1
	v_pk_mul_f32 v[10:11], v[10:11], v[22:23]
	v_cvt_pk_bf16_f32 v8, v8, v9
	v_mov_b32_e32 v23, v7
	v_add_f32_e32 v1, 1.0, v1
	v_rcp_f32_e32 v21, v1
	v_mov_b32_e32 v22, v6
	v_pk_mul_f32 v[18:19], v[20:21], v[18:19]
	s_nop 0
	v_pk_mul_f32 v[10:11], v[10:11], v[18:19]
	s_nop 0
	v_cvt_pk_bf16_f32 v9, v10, v11
	global_store_dwordx2 v[12:13], v[8:9], off offset:576 sc0 sc1
	v_mov_b64_e32 v[8:9], v[242:243]
	v_mov_b64_e32 v[10:11], v[244:245]
	v_mov_b64_e32 v[14:15], v[246:247]
	v_lshlrev_b32_e32 v16, 16, v14
	v_mul_f32_e32 v1, 0xbfb8aa3b, v16
	v_exp_f32_e32 v1, v1
	v_and_b32_e32 v17, 0xffff0000, v14
	v_lshlrev_b32_e32 v14, 16, v15
	v_and_b32_e32 v15, 0xffff0000, v15
	v_add_f32_e32 v1, 1.0, v1
	v_rcp_f32_e32 v18, v1
	v_pk_mul_f32 v[20:21], v[44:45], v[0:1] op_sel_hi:[1,0]
	v_mul_f32_e32 v1, 0xbfb8aa3b, v17
	v_exp_f32_e32 v1, v1
	v_mul_f32_e32 v2, 0xbfb8aa3b, v15
	v_exp_f32_e32 v2, v2
	v_pk_mul_f32 v[8:9], v[20:21], v[8:9]
	v_add_f32_e32 v1, 1.0, v1
	v_rcp_f32_e32 v19, v1
	v_mul_f32_e32 v1, 0xbfb8aa3b, v14
	v_exp_f32_e32 v1, v1
	v_add_f32_e32 v2, 1.0, v2
	v_pk_mul_f32 v[16:17], v[18:19], v[16:17]
	v_mov_b32_e32 v19, v59
	v_add_f32_e32 v1, 1.0, v1
	v_pk_mul_f32 v[8:9], v[8:9], v[16:17]
	v_rcp_f32_e32 v16, v1
	v_rcp_f32_e32 v17, v2
	v_pk_mul_f32 v[0:1], v[46:47], v[0:1] op_sel_hi:[1,0]
	v_cvt_pk_bf16_f32 v8, v8, v9
	v_pk_mul_f32 v[0:1], v[0:1], v[10:11]
	v_pk_mul_f32 v[10:11], v[16:17], v[14:15]
	v_mov_b32_e32 v18, v58
	v_pk_mul_f32 v[0:1], v[0:1], v[10:11]
	v_mov_b32_e32 v17, v57
	v_cvt_pk_bf16_f32 v9, v0, v1
	global_store_dwordx2 v[12:13], v[8:9], off offset:608 sc0 sc1
	v_mov_b32_e32 v16, v56
	v_mov_b32_e32 v15, v39
	v_mov_b32_e32 v14, v38
	v_mov_b32_e32 v13, v37
	v_mov_b32_e32 v12, v36
	v_mov_b32_e32 v11, v83
	v_mov_b32_e32 v21, v5
	v_mov_b32_e32 v20, v4

.LBB0_745:
	s_and_b64 s[2:3], s[38:39], s[66:67]
	s_and_b64 vcc, exec, s[2:3]
	v_readlane_b32 s43, v253, 58
	s_cbranch_vccz .LBB0_747
	s_add_i32 s92, s42, 32
	s_lshl_b64 s[2:3], s[92:93], 13
	s_add_u32 s0, s72, s2
	s_addc_u32 s3, s73, s3
	s_lshl_b32 s2, s55, 1
	v_ashrrev_i32_e32 v0, 2, v168
	s_add_u32 s2, s0, s2
	v_and_b32_e32 v0, -4, v0
	s_addc_u32 s3, s3, 0
	v_ashrrev_i32_e32 v1, 31, v0
	v_lshlrev_b32_e32 v2, 7, v168
	v_lshl_add_u64 v[0:1], v[0:1], 1, s[2:3]
	v_and_b32_e32 v2, 0x780, v2
	v_lshl_add_u64 v[0:1], v[0:1], 0, v[2:3]
	s_mov_b32 s0, 0xdbac000
	v_add_co_u32_e32 v8, vcc, s0, v0
	v_cvt_pk_bf16_f32 v4, v112, v113
	v_cvt_pk_bf16_f32 v5, v114, v115
	s_mov_b64 s[2:3], 0xdbac000
	v_addc_co_u32_e32 v9, vcc, 0, v1, vcc
	v_lshl_add_u64 v[6:7], v[0:1], 0, s[2:3]
	global_store_dwordx2 v[8:9], v[4:5], off sc0 sc1
	v_cvt_pk_bf16_f32 v4, v120, v121
	v_cvt_pk_bf16_f32 v5, v122, v123
	v_add_co_u32_e32 v0, vcc, 0xdbad000, v0
	global_store_dwordx2 v[6:7], v[4:5], off offset:2048 sc0 sc1
	v_cvt_pk_bf16_f32 v4, v116, v117
	v_cvt_pk_bf16_f32 v5, v118, v119
	v_addc_co_u32_e32 v1, vcc, 0, v1, vcc
	global_store_dwordx2 v[0:1], v[4:5], off sc0 sc1
	v_cvt_pk_bf16_f32 v4, v108, v109
	v_cvt_pk_bf16_f32 v5, v110, v111
	global_store_dwordx2 v[0:1], v[4:5], off offset:2048 sc0 sc1

.LBB0_772:
	v_mul_f32_e32 v54, 0x3fb8aa3b, v2
	v_exp_f32_e32 v54, v54
	v_cndmask_b32_e64 v55, 0, 1, s[28:29]
	v_cmp_ne_u32_e64 s[20:21], 1, v55
	s_andn2_b64 vcc, exec, s[28:29]
	v_mul_f32_e32 v54, v95, v54
	v_cvt_pk_bf16_f32 v54, v54, s0
	ds_write_b16 v172, v54 offset:27648
	v_lshl_add_u64 v[54:55], s[72:73], 0, v[92:93]
	s_cbranch_vccnz .LBB0_774
	v_add_f32_e32 v57, v196, v2
	v_mul_f32_e32 v57, 0x3fb8aa3b, v57
	v_exp_f32_e32 v57, v57
	s_nop 0
	v_mul_f32_e32 v57, v95, v57
	v_cvt_pk_bf16_f32 v57, v57, s0
	global_store_short v[54:55], v57, off offset:-1024 sc0 sc1

.LBB0_776:
	v_mul_f32_e32 v60, 0x3fb8aa3b, v57
	v_exp_f32_e32 v60, v60
	s_and_b64 vcc, exec, s[20:21]
	v_mul_f32_e32 v60, v94, v60
	v_cvt_pk_bf16_f32 v60, v60, s0
	ds_write_b16 v174, v60 offset:27648
	s_cbranch_vccnz .LBB0_778
	v_add_f32_e32 v60, v196, v57
	v_mul_f32_e32 v60, 0x3fb8aa3b, v60
	v_exp_f32_e32 v60, v60
	s_nop 0
	v_mul_f32_e32 v60, v94, v60
	v_cvt_pk_bf16_f32 v60, v60, s0
	global_store_short v[54:55], v60, off offset:-896 sc0 sc1

.LBB0_780:
	v_mul_f32_e32 v61, 0x3fb8aa3b, v60
	v_exp_f32_e32 v61, v61
	s_and_b64 vcc, exec, s[20:21]
	v_mul_f32_e32 v61, v99, v61
	v_cvt_pk_bf16_f32 v61, v61, s0
	ds_write_b16 v175, v61 offset:27648
	s_cbranch_vccnz .LBB0_782
	v_add_f32_e32 v61, v196, v60
	v_mul_f32_e32 v61, 0x3fb8aa3b, v61
	v_exp_f32_e32 v61, v61
	s_nop 0
	v_mul_f32_e32 v61, v99, v61
	v_cvt_pk_bf16_f32 v61, v61, s0
	global_store_short v[54:55], v61, off offset:-768 sc0 sc1

.LBB0_784:
	v_mul_f32_e32 v62, 0x3fb8aa3b, v61
	v_exp_f32_e32 v62, v62
	s_and_b64 vcc, exec, s[20:21]
	v_mul_f32_e32 v62, v98, v62
	v_cvt_pk_bf16_f32 v62, v62, s0
	ds_write_b16 v176, v62 offset:27648
	s_cbranch_vccnz .LBB0_786
	v_add_f32_e32 v62, v196, v61
	v_mul_f32_e32 v62, 0x3fb8aa3b, v62
	v_exp_f32_e32 v62, v62
	s_nop 0
	v_mul_f32_e32 v62, v98, v62
	v_cvt_pk_bf16_f32 v62, v62, s0
	global_store_short v[54:55], v62, off offset:-640 sc0 sc1

.LBB0_788:
	v_mul_f32_e32 v63, 0x3fb8aa3b, v62
	v_exp_f32_e32 v63, v63
	s_and_b64 vcc, exec, s[20:21]
	v_mul_f32_e32 v63, v103, v63
	v_cvt_pk_bf16_f32 v63, v63, s0
	ds_write_b16 v177, v63 offset:27648
	s_cbranch_vccnz .LBB0_790
	v_add_f32_e32 v63, v196, v62
	v_mul_f32_e32 v63, 0x3fb8aa3b, v63
	v_exp_f32_e32 v63, v63
	s_nop 0
	v_mul_f32_e32 v63, v103, v63
	v_cvt_pk_bf16_f32 v63, v63, s0
	global_store_short v[54:55], v63, off offset:-512 sc0 sc1

.LBB0_792:
	v_mul_f32_e32 v64, 0x3fb8aa3b, v63
	v_exp_f32_e32 v64, v64
	s_and_b64 vcc, exec, s[20:21]
	v_mul_f32_e32 v64, v102, v64
	v_cvt_pk_bf16_f32 v64, v64, s0
	ds_write_b16 v178, v64 offset:27648
	s_cbranch_vccnz .LBB0_794
	v_add_f32_e32 v64, v196, v63
	v_mul_f32_e32 v64, 0x3fb8aa3b, v64
	v_exp_f32_e32 v64, v64
	s_nop 0
	v_mul_f32_e32 v64, v102, v64
	v_cvt_pk_bf16_f32 v64, v64, s0
	global_store_short v[54:55], v64, off offset:-384 sc0 sc1

.LBB0_796:
	v_mul_f32_e32 v65, 0x3fb8aa3b, v64
	v_exp_f32_e32 v65, v65
	s_and_b64 vcc, exec, s[20:21]
	v_mul_f32_e32 v65, v107, v65
	v_cvt_pk_bf16_f32 v65, v65, s0
	ds_write_b16 v179, v65 offset:27648
	s_cbranch_vccnz .LBB0_798
	v_add_f32_e32 v65, v196, v64
	v_mul_f32_e32 v65, 0x3fb8aa3b, v65
	v_exp_f32_e32 v65, v65
	s_nop 0
	v_mul_f32_e32 v65, v107, v65
	v_cvt_pk_bf16_f32 v65, v65, s0
	global_store_short v[54:55], v65, off offset:-256 sc0 sc1

.LBB0_800:
	v_mul_f32_e32 v66, 0x3fb8aa3b, v65
	v_exp_f32_e32 v66, v66
	s_and_b64 vcc, exec, s[20:21]
	v_mul_f32_e32 v66, v106, v66
	v_cvt_pk_bf16_f32 v66, v66, s0
	ds_write_b16 v180, v66 offset:27648
	s_cbranch_vccnz .LBB0_802
	v_add_f32_e32 v66, v196, v65
	v_mul_f32_e32 v66, 0x3fb8aa3b, v66
	v_exp_f32_e32 v66, v66
	s_nop 0
	v_mul_f32_e32 v66, v106, v66
	v_cvt_pk_bf16_f32 v66, v66, s0
	global_store_short v[54:55], v66, off offset:-128 sc0 sc1

.LBB0_804:
	v_mul_f32_e32 v67, 0x3fb8aa3b, v66
	v_exp_f32_e32 v67, v67
	s_and_b64 vcc, exec, s[20:21]
	v_mul_f32_e32 v67, v111, v67
	v_cvt_pk_bf16_f32 v67, v67, s0
	ds_write_b16 v181, v67 offset:27648
	s_cbranch_vccnz .LBB0_806
	v_add_f32_e32 v67, v196, v66
	v_mul_f32_e32 v67, 0x3fb8aa3b, v67
	v_exp_f32_e32 v67, v67
	s_nop 0
	v_mul_f32_e32 v67, v111, v67
	v_cvt_pk_bf16_f32 v67, v67, s0
	global_store_short v[54:55], v67, off sc0 sc1

.LBB0_808:
	v_mul_f32_e32 v68, 0x3fb8aa3b, v67
	v_exp_f32_e32 v68, v68
	s_and_b64 vcc, exec, s[20:21]
	v_mul_f32_e32 v68, v110, v68
	v_cvt_pk_bf16_f32 v68, v68, s0
	ds_write_b16 v182, v68 offset:27648
	s_cbranch_vccnz .LBB0_810
	v_add_f32_e32 v68, v196, v67
	v_mul_f32_e32 v68, 0x3fb8aa3b, v68
	v_exp_f32_e32 v68, v68
	s_nop 0
	v_mul_f32_e32 v68, v110, v68
	v_cvt_pk_bf16_f32 v68, v68, s0
	global_store_short v[54:55], v68, off offset:128 sc0 sc1

.LBB0_812:
	v_mul_f32_e32 v69, 0x3fb8aa3b, v68
	v_exp_f32_e32 v69, v69
	s_and_b64 vcc, exec, s[20:21]
	v_mul_f32_e32 v69, v115, v69
	v_cvt_pk_bf16_f32 v69, v69, s0
	ds_write_b16 v184, v69 offset:27648
	s_cbranch_vccnz .LBB0_814
	v_add_f32_e32 v69, v196, v68
	v_mul_f32_e32 v69, 0x3fb8aa3b, v69
	v_exp_f32_e32 v69, v69
	s_nop 0
	v_mul_f32_e32 v69, v115, v69
	v_cvt_pk_bf16_f32 v69, v69, s0
	global_store_short v[54:55], v69, off offset:256 sc0 sc1

.LBB0_816:
	v_mul_f32_e32 v70, 0x3fb8aa3b, v69
	v_exp_f32_e32 v70, v70
	s_and_b64 vcc, exec, s[20:21]
	v_mul_f32_e32 v70, v114, v70
	v_cvt_pk_bf16_f32 v70, v70, s0
	ds_write_b16 v186, v70 offset:27648
	s_cbranch_vccnz .LBB0_818
	v_add_f32_e32 v70, v196, v69
	v_mul_f32_e32 v70, 0x3fb8aa3b, v70
	v_exp_f32_e32 v70, v70
	s_nop 0
	v_mul_f32_e32 v70, v114, v70
	v_cvt_pk_bf16_f32 v70, v70, s0
	global_store_short v[54:55], v70, off offset:384 sc0 sc1

.LBB0_820:
	v_mul_f32_e32 v71, 0x3fb8aa3b, v70
	v_exp_f32_e32 v71, v71
	s_and_b64 vcc, exec, s[20:21]
	v_mul_f32_e32 v71, v119, v71
	v_cvt_pk_bf16_f32 v71, v71, s0
	ds_write_b16 v187, v71 offset:27648
	s_cbranch_vccnz .LBB0_822
	v_add_f32_e32 v71, v196, v70
	v_mul_f32_e32 v71, 0x3fb8aa3b, v71
	v_exp_f32_e32 v71, v71
	s_nop 0
	v_mul_f32_e32 v71, v119, v71
	v_cvt_pk_bf16_f32 v71, v71, s0
	global_store_short v[54:55], v71, off offset:512 sc0 sc1

.LBB0_824:
	v_mul_f32_e32 v219, 0x3fb8aa3b, v71
	v_exp_f32_e32 v219, v219
	s_and_b64 vcc, exec, s[20:21]
	v_mul_f32_e32 v219, v118, v219
	v_cvt_pk_bf16_f32 v219, v219, s0
	ds_write_b16 v188, v219 offset:27648
	s_cbranch_vccnz .LBB0_826
	v_add_f32_e32 v219, v196, v71
	v_mul_f32_e32 v219, 0x3fb8aa3b, v219
	v_exp_f32_e32 v219, v219
	s_nop 0
	v_mul_f32_e32 v219, v118, v219
	v_cvt_pk_bf16_f32 v219, v219, s0
	global_store_short v[54:55], v219, off offset:640 sc0 sc1

.LBB0_828:
	v_mul_f32_e32 v220, 0x3fb8aa3b, v219
	v_exp_f32_e32 v220, v220
	s_and_b64 vcc, exec, s[20:21]
	v_mul_f32_e32 v220, v123, v220
	v_cvt_pk_bf16_f32 v220, v220, s0
	ds_write_b16 v189, v220 offset:27648
	s_cbranch_vccnz .LBB0_830
	v_add_f32_e32 v220, v196, v219
	v_mul_f32_e32 v220, 0x3fb8aa3b, v220
	v_exp_f32_e32 v220, v220
	s_nop 0
	v_mul_f32_e32 v220, v123, v220
	v_cvt_pk_bf16_f32 v220, v220, s0
	global_store_short v[54:55], v220, off offset:768 sc0 sc1

.LBB0_832:
	v_mul_f32_e32 v59, 0x3fb8aa3b, v58
	v_exp_f32_e32 v59, v59
	s_and_b64 vcc, exec, s[20:21]
	v_mul_f32_e32 v59, v122, v59
	v_cvt_pk_bf16_f32 v59, v59, s0
	ds_write_b16 v190, v59 offset:27648
	s_cbranch_vccnz .LBB0_834
	v_add_f32_e32 v59, v196, v58
	v_mul_f32_e32 v59, 0x3fb8aa3b, v59
	v_exp_f32_e32 v59, v59
	s_nop 0
	v_mul_f32_e32 v59, v122, v59
	v_cvt_pk_bf16_f32 v59, v59, s0
	global_store_short v[54:55], v59, off offset:896 sc0 sc1

.LBB0_848:
	ds_read_b128 v[68:71], v198 offset:27648
	ds_read_b128 v[220:223], v202 offset:55296
	s_mov_b64 s[16:17], -1
	s_and_b64 vcc, exec, s[28:29]
	s_waitcnt lgkmcnt(0)
	v_mfma_f32_16x16x32_bf16 v[52:55], v[220:223], v[68:71], v[52:55]
	ds_read_b128 v[220:223], v202 offset:57600
	s_waitcnt lgkmcnt(0)
	v_mfma_f32_16x16x32_bf16 v[56:59], v[220:223], v[68:71], v[56:59]
	ds_read_b128 v[220:223], v202 offset:59904
	s_waitcnt lgkmcnt(0)
	v_mfma_f32_16x16x32_bf16 v[220:223], v[220:223], v[68:71], v[60:63]
	s_nop 2
	ds_read_b128 v[60:63], v202 offset:62208
	s_waitcnt lgkmcnt(0)
	v_mfma_f32_16x16x32_bf16 v[68:71], v[60:63], v[68:71], v[64:67]
	ds_read_b128 v[224:227], v198 offset:27712
	ds_read_b128 v[60:63], v202 offset:55360
	s_waitcnt lgkmcnt(0)
	v_mfma_f32_16x16x32_bf16 v[64:67], v[60:63], v[224:227], v[52:55]
	s_nop 2
	ds_read_b128 v[52:55], v202 offset:57664
	s_waitcnt lgkmcnt(0)
	v_mfma_f32_16x16x32_bf16 v[60:63], v[52:55], v[224:227], v[56:59]
	ds_read_b128 v[52:55], v202 offset:59968
	s_waitcnt lgkmcnt(0)
	v_mfma_f32_16x16x32_bf16 v[56:59], v[52:55], v[224:227], v[220:223]
	ds_read_b128 v[52:55], v202 offset:62272
	s_waitcnt lgkmcnt(0)
	v_mfma_f32_16x16x32_bf16 v[52:55], v[52:55], v[224:227], v[68:71]
	s_cbranch_vccz .LBB0_850
	s_nop 1
	v_lshl_add_u64 v[68:69], s[72:73], 0, v[90:91]
	v_cvt_pk_bf16_f32 v70, v64, v65
	v_cvt_pk_bf16_f32 v71, v66, v67
	global_store_dwordx2 v[68:69], v[70:71], off offset:-64 sc0 sc1
	v_cvt_pk_bf16_f32 v70, v60, v61
	v_cvt_pk_bf16_f32 v71, v62, v63
	global_store_dwordx2 v[68:69], v[70:71], off offset:-32 sc0 sc1
	v_cvt_pk_bf16_f32 v70, v56, v57
	v_cvt_pk_bf16_f32 v71, v58, v59
	global_store_dwordx2 v[68:69], v[70:71], off sc0 sc1
	v_cvt_pk_bf16_f32 v70, v52, v53
	v_cvt_pk_bf16_f32 v71, v54, v55
	global_store_dwordx2 v[68:69], v[70:71], off offset:32 sc0 sc1
	s_mov_b64 s[16:17], 0
.LBB0_850:
	s_andn2_b64 vcc, exec, s[16:17]
	s_cbranch_vccnz .LBB0_763
	v_pk_mul_f32 v[68:69], v[66:67], v[66:67]
	v_pk_mul_f32 v[70:71], v[64:65], v[64:65]
	s_nop 2
	v_mul_f32_e32 v2, v52, v52
	v_pk_mov_b32 v[220:221], v[70:71], v[68:69] op_sel:[1,0]
	v_mov_b32_e32 v71, v69
	v_pk_add_f32 v[68:69], v[220:221], v[70:71]
	v_pk_mul_f32 v[70:71], v[62:63], v[62:63]
	v_pk_mul_f32 v[220:221], v[60:61], v[60:61]
	v_mul_f32_e32 v219, v53, v53
	v_pk_mov_b32 v[222:223], v[220:221], v[70:71] op_sel:[1,0]
	v_mov_b32_e32 v221, v71
	v_pk_add_f32 v[70:71], v[222:223], v[220:221]
	v_pk_add_f32 v[68:69], v[68:69], v[68:69] op_sel:[0,1] op_sel_hi:[1,0]
	v_pk_add_f32 v[70:71], v[70:71], v[70:71] op_sel:[0,1] op_sel_hi:[1,0]
	v_mov_b32_e32 v69, v2
	v_mov_b32_e32 v71, v219
	v_mul_f32_e32 v2, v57, v57
	v_mul_f32_e32 v220, v54, v54
	v_pk_add_f32 v[68:69], v[68:69], v[70:71]
	v_pk_fma_f32 v[70:71], v[56:57], v[56:57], v[2:3] op_sel_hi:[1,1,0]
	v_mul_f32_e32 v2, v59, v59
	v_mul_f32_e32 v222, v55, v55
	v_mov_b32_e32 v71, v220
	v_pk_fma_f32 v[220:221], v[58:59], v[58:59], v[2:3] op_sel_hi:[1,1,0]
	s_nop 0
	v_mov_b32_e32 v221, v222
	v_pk_add_f32 v[70:71], v[70:71], v[220:221]
	s_nop 0
	v_pk_add_f32 v[68:69], v[68:69], v[70:71]
	s_nop 0
	v_add_f32_e32 v2, v68, v69
	v_and_b32_e32 v69, 64, v234
	v_xor_b32_e32 v68, 16, v234
	v_add_u32_e32 v69, 64, v69
	v_cmp_lt_i32_e32 vcc, v68, v69
	s_nop 1
	v_cndmask_b32_e32 v68, v234, v68, vcc
	v_lshlrev_b32_e32 v68, 2, v68
	ds_bpermute_b32 v68, v68, v2
	s_waitcnt lgkmcnt(0)
	v_add_f32_e32 v2, v2, v68
	v_xor_b32_e32 v68, 32, v234
	v_cmp_lt_i32_e32 vcc, v68, v69
	s_nop 1
	v_cndmask_b32_e32 v68, v234, v68, vcc
	v_lshlrev_b32_e32 v68, 2, v68
	ds_bpermute_b32 v68, v68, v2
	s_waitcnt lgkmcnt(0)
	v_add_f32_e32 v2, v2, v68
	v_fmamk_f32 v2, v2, 0x3c800000, v158
	v_cmp_gt_f32_e32 vcc, s75, v2
	v_mul_f32_e32 v68, 0x4b800000, v2
	s_nop 0
	v_cndmask_b32_e32 v2, v2, v68, vcc
	v_rsq_f32_e32 v2, v2
	s_nop 0
	v_mul_f32_e32 v68, 0x45800000, v2
	v_cndmask_b32_e32 v2, v2, v68, vcc
	v_pk_mul_f32 v[64:65], v[64:65], v[2:3] op_sel_hi:[1,0]
	v_pk_mul_f32 v[66:67], v[66:67], v[2:3] op_sel_hi:[1,0]
	v_pk_mul_f32 v[64:65], v[20:21], v[64:65]
	v_pk_mul_f32 v[66:67], v[22:23], v[66:67]
	v_pk_mul_f32 v[60:61], v[60:61], v[2:3] op_sel_hi:[1,0]
	v_pk_mul_f32 v[62:63], v[62:63], v[2:3] op_sel_hi:[1,0]
	v_pk_mul_f32 v[60:61], v[24:25], v[60:61]
	v_pk_mul_f32 v[62:63], v[26:27], v[62:63]
	v_pk_mul_f32 v[56:57], v[56:57], v[2:3] op_sel_hi:[1,0]
	v_pk_mul_f32 v[58:59], v[58:59], v[2:3] op_sel_hi:[1,0]
	v_pk_mul_f32 v[56:57], v[28:29], v[56:57]
	v_pk_mul_f32 v[58:59], v[30:31], v[58:59]
	v_pk_mul_f32 v[52:53], v[52:53], v[2:3] op_sel_hi:[1,0]
	v_pk_mul_f32 v[54:55], v[54:55], v[2:3] op_sel_hi:[1,0]
	v_pk_mul_f32 v[52:53], v[32:33], v[52:53]
	v_pk_mul_f32 v[54:55], v[34:35], v[54:55]
	s_waitcnt vmcnt(0)
	v_lshlrev_b32_e32 v70, 16, v242
	v_and_b32_e32 v71, 0xffff0000, v242
	v_mul_f32_e32 v68, 0xbfb8aa3b, v70
	v_exp_f32_e32 v68, v68
	s_nop 0
	v_add_f32_e32 v68, 1.0, v68
	v_rcp_f32_e32 v220, v68
	v_mul_f32_e32 v68, 0xbfb8aa3b, v71
	v_exp_f32_e32 v68, v68
	s_nop 0
	v_add_f32_e32 v68, 1.0, v68
	v_rcp_f32_e32 v221, v68
	s_nop 0
	v_pk_mul_f32 v[70:71], v[220:221], v[70:71]
	s_nop 0
	v_pk_mul_f32 v[64:65], v[70:71], v[64:65]
	s_nop 0
	v_cvt_pk_bf16_f32 v68, v64, v65
	v_lshlrev_b32_e32 v64, 16, v243
	v_and_b32_e32 v65, 0xffff0000, v243
	v_mul_f32_e32 v69, 0xbfb8aa3b, v64
	v_exp_f32_e32 v69, v69
	s_nop 0
	v_add_f32_e32 v69, 1.0, v69
	v_rcp_f32_e32 v70, v69
	v_mul_f32_e32 v69, 0xbfb8aa3b, v65
	v_exp_f32_e32 v69, v69
	s_nop 0
	v_add_f32_e32 v69, 1.0, v69
	v_rcp_f32_e32 v71, v69
	s_nop 0
	v_pk_mul_f32 v[64:65], v[70:71], v[64:65]
	s_nop 0
	v_pk_mul_f32 v[64:65], v[64:65], v[66:67]
	v_cvt_pk_bf16_f32 v69, v64, v65
	v_lshl_add_u64 v[64:65], s[72:73], 0, v[88:89]
	global_store_dwordx2 v[64:65], v[68:69], off offset:-64 sc0 sc1
	v_lshlrev_b32_e32 v68, 16, v244
	v_and_b32_e32 v69, 0xffff0000, v244
	v_mul_f32_e32 v66, 0xbfb8aa3b, v68
	v_exp_f32_e32 v66, v66
	s_nop 0
	v_add_f32_e32 v66, 1.0, v66
	v_rcp_f32_e32 v70, v66
	v_mul_f32_e32 v66, 0xbfb8aa3b, v69
	v_exp_f32_e32 v66, v66
	s_nop 0
	v_add_f32_e32 v66, 1.0, v66
	v_rcp_f32_e32 v71, v66
	v_lshlrev_b32_e32 v66, 16, v245
	v_and_b32_e32 v67, 0xffff0000, v245
	v_pk_mul_f32 v[68:69], v[70:71], v[68:69]
	s_nop 0
	v_pk_mul_f32 v[60:61], v[60:61], v[68:69]
	s_nop 0
	v_cvt_pk_bf16_f32 v60, v60, v61
	v_mul_f32_e32 v61, 0xbfb8aa3b, v66
	v_exp_f32_e32 v61, v61
	s_nop 0
	v_add_f32_e32 v61, 1.0, v61
	v_rcp_f32_e32 v68, v61
	v_mul_f32_e32 v61, 0xbfb8aa3b, v67
	v_exp_f32_e32 v61, v61
	s_nop 0
	v_add_f32_e32 v61, 1.0, v61
	v_rcp_f32_e32 v69, v61
	s_nop 0
	v_pk_mul_f32 v[66:67], v[68:69], v[66:67]
	s_nop 0
	v_pk_mul_f32 v[62:63], v[62:63], v[66:67]
	s_nop 0
	v_cvt_pk_bf16_f32 v61, v62, v63
	global_store_dwordx2 v[64:65], v[60:61], off offset:-32 sc0 sc1
	v_lshlrev_b32_e32 v62, 16, v246
	v_and_b32_e32 v63, 0xffff0000, v246
	v_mul_f32_e32 v60, 0xbfb8aa3b, v62
	v_exp_f32_e32 v60, v60
	s_nop 0
	v_add_f32_e32 v60, 1.0, v60
	v_rcp_f32_e32 v66, v60
	v_mul_f32_e32 v60, 0xbfb8aa3b, v63
	v_exp_f32_e32 v60, v60
	s_nop 0
	v_add_f32_e32 v60, 1.0, v60
	v_rcp_f32_e32 v67, v60
	v_lshlrev_b32_e32 v60, 16, v247
	v_and_b32_e32 v61, 0xffff0000, v247
	v_pk_mul_f32 v[62:63], v[66:67], v[62:63]
	s_nop 0
	v_pk_mul_f32 v[56:57], v[56:57], v[62:63]
	s_nop 0
	v_cvt_pk_bf16_f32 v56, v56, v57
	v_mul_f32_e32 v57, 0xbfb8aa3b, v60
	v_exp_f32_e32 v57, v57
	s_nop 0
	v_add_f32_e32 v57, 1.0, v57
	v_rcp_f32_e32 v62, v57
	v_mul_f32_e32 v57, 0xbfb8aa3b, v61
	v_exp_f32_e32 v57, v57
	s_nop 0
	v_add_f32_e32 v57, 1.0, v57
	v_rcp_f32_e32 v63, v57
	s_nop 0
	v_pk_mul_f32 v[60:61], v[62:63], v[60:61]
	s_nop 0
	v_pk_mul_f32 v[58:59], v[58:59], v[60:61]
	s_nop 0
	v_cvt_pk_bf16_f32 v57, v58, v59
	global_store_dwordx2 v[64:65], v[56:57], off sc0 sc1
	v_lshlrev_b32_e32 v58, 16, v248
	v_and_b32_e32 v59, 0xffff0000, v248
	v_mul_f32_e32 v56, 0xbfb8aa3b, v58
	v_exp_f32_e32 v56, v56
	s_nop 0
	v_add_f32_e32 v56, 1.0, v56
	v_rcp_f32_e32 v60, v56
	v_mul_f32_e32 v56, 0xbfb8aa3b, v59
	v_exp_f32_e32 v56, v56
	s_nop 0
	v_add_f32_e32 v56, 1.0, v56
	v_rcp_f32_e32 v61, v56
	v_lshlrev_b32_e32 v56, 16, v249
	v_and_b32_e32 v57, 0xffff0000, v249
	v_mul_f32_e32 v2, 0xbfb8aa3b, v57
	v_pk_mul_f32 v[58:59], v[60:61], v[58:59]
	v_exp_f32_e32 v2, v2
	v_pk_mul_f32 v[52:53], v[52:53], v[58:59]
	v_add_f32_e32 v2, 1.0, v2
	v_cvt_pk_bf16_f32 v52, v52, v53
	v_mul_f32_e32 v53, 0xbfb8aa3b, v56
	v_exp_f32_e32 v53, v53
	v_rcp_f32_e32 v59, v2
	v_add_f32_e32 v53, 1.0, v53
	v_rcp_f32_e32 v58, v53
	s_nop 0
	v_pk_mul_f32 v[56:57], v[58:59], v[56:57]
	s_nop 0
	v_pk_mul_f32 v[54:55], v[54:55], v[56:57]
	s_nop 0
	v_cvt_pk_bf16_f32 v53, v54, v55
	global_store_dwordx2 v[64:65], v[52:53], off offset:32 sc0 sc1
	s_branch .LBB0_763
.LBB0_852:
	s_and_b64 s[2:3], s[26:27], s[24:25]
	s_andn2_b64 vcc, exec, s[2:3]
	s_cbranch_vccnz .LBB0_854
	s_lshl_b64 s[2:3], s[66:67], 13
	s_add_u32 s2, s72, s2
	s_addc_u32 s3, s73, s3
	s_lshl_b32 s1, s1, 5
	s_add_u32 s2, s2, s1
	s_addc_u32 s3, s3, 0
	v_mov_b32_e32 v75, v3
	v_lshl_add_u64 v[0:1], s[2:3], 0, v[74:75]
	v_lshlrev_b32_e32 v2, 7, v149
	v_lshl_add_u64 v[0:1], v[0:1], 0, v[2:3]
	s_mov_b32 s1, 0xdbac000
	v_add_co_u32_e32 v8, vcc, s1, v0
	v_cvt_pk_bf16_f32 v4, v44, v45
	v_cvt_pk_bf16_f32 v5, v46, v47
	s_mov_b64 s[2:3], 0xdbac000
	v_addc_co_u32_e32 v9, vcc, 0, v1, vcc
	v_lshl_add_u64 v[6:7], v[0:1], 0, s[2:3]
	global_store_dwordx2 v[8:9], v[4:5], off sc0 sc1
	v_cvt_pk_bf16_f32 v4, v48, v49
	v_cvt_pk_bf16_f32 v5, v50, v51
	v_add_co_u32_e32 v0, vcc, 0xdbad000, v0
	global_store_dwordx2 v[6:7], v[4:5], off offset:2048 sc0 sc1
	v_cvt_pk_bf16_f32 v4, v40, v41
	v_cvt_pk_bf16_f32 v5, v42, v43
	v_addc_co_u32_e32 v1, vcc, 0, v1, vcc
	global_store_dwordx2 v[0:1], v[4:5], off sc0 sc1
	v_cvt_pk_bf16_f32 v4, v36, v37
	v_cvt_pk_bf16_f32 v5, v38, v39
	global_store_dwordx2 v[0:1], v[4:5], off offset:2048 sc0 sc1

.LBB0_906:
	s_waitcnt lgkmcnt(0)
	ds_read2_b32 v[56:57], v54 offset1:8
	ds_read2_b32 v[58:59], v54 offset0:33 offset1:41
	ds_read2_b32 v[60:61], v54 offset0:66 offset1:74
	ds_read2_b32 v[62:63], v54 offset0:99 offset1:107
	v_mov_b32_e32 v43, v3
	v_lshl_add_u64 v[44:45], v[44:45], 0, v[42:43]
	s_waitcnt lgkmcnt(3)
	v_bfe_u32 v2, v56, 16, 1
	v_add3_u32 v2, v56, v2, s62
	s_waitcnt lgkmcnt(2)
	v_bfe_u32 v43, v58, 16, 1
	ds_read2_b32 v[64:65], v54 offset0:132 offset1:140
	v_lshrrev_b32_e32 v2, 16, v2
	v_add3_u32 v43, v58, v43, s62
	ds_read2_b32 v[66:67], v54 offset0:165 offset1:173
	v_and_or_b32 v48, v43, s33, v2
	s_waitcnt lgkmcnt(3)
	v_bfe_u32 v2, v60, 16, 1
	v_add3_u32 v2, v60, v2, s62
	s_waitcnt lgkmcnt(2)
	v_bfe_u32 v43, v62, 16, 1
	ds_read2_b32 v[68:69], v54 offset0:198 offset1:206
	v_lshrrev_b32_e32 v2, 16, v2
	v_add3_u32 v43, v62, v43, s62
	ds_read2_b32 v[70:71], v54 offset0:231 offset1:239
	v_and_or_b32 v49, v43, s33, v2
	s_waitcnt lgkmcnt(3)
	v_bfe_u32 v2, v64, 16, 1
	v_add3_u32 v2, v64, v2, s62
	s_waitcnt lgkmcnt(2)
	v_bfe_u32 v43, v66, 16, 1
	v_lshrrev_b32_e32 v2, 16, v2
	v_add3_u32 v43, v66, v43, s62
	v_and_or_b32 v50, v43, s33, v2
	s_waitcnt lgkmcnt(1)
	v_bfe_u32 v2, v68, 16, 1
	v_add3_u32 v2, v68, v2, s62
	s_waitcnt lgkmcnt(0)
	v_bfe_u32 v43, v70, 16, 1
	v_lshrrev_b32_e32 v2, 16, v2
	v_add3_u32 v43, v70, v43, s62
	v_and_or_b32 v51, v43, s33, v2
	v_bfe_u32 v2, v57, 16, 1
	v_add3_u32 v2, v57, v2, s62
	v_bfe_u32 v43, v59, 16, 1
	v_lshl_add_u64 v[72:73], v[44:45], 0, v[0:1]
	v_lshrrev_b32_e32 v2, 16, v2
	v_add3_u32 v43, v59, v43, s62
	global_store_dwordx4 v[72:73], v[48:51], off sc0 sc1
	ds_read2_b32 v[56:57], v54 offset0:16 offset1:24
	v_lshl_add_u64 v[58:59], v[44:45], 0, v[36:37]
	v_and_or_b32 v48, v43, s33, v2
	v_bfe_u32 v2, v61, 16, 1
	v_add3_u32 v2, v61, v2, s62
	v_bfe_u32 v43, v63, 16, 1
	v_lshrrev_b32_e32 v2, 16, v2
	v_add3_u32 v43, v63, v43, s62
	v_and_or_b32 v49, v43, s33, v2
	v_bfe_u32 v2, v65, 16, 1
	v_add3_u32 v2, v65, v2, s62
	v_bfe_u32 v43, v67, 16, 1
	v_lshrrev_b32_e32 v2, 16, v2
	v_add3_u32 v43, v67, v43, s62
	v_and_or_b32 v50, v43, s33, v2
	v_bfe_u32 v2, v69, 16, 1
	v_add3_u32 v2, v69, v2, s62
	v_bfe_u32 v43, v71, 16, 1
	v_lshrrev_b32_e32 v2, 16, v2
	v_add3_u32 v43, v71, v43, s62
	v_and_or_b32 v51, v43, s33, v2
	global_store_dwordx4 v[58:59], v[48:51], off sc0 sc1
	ds_read2_b32 v[58:59], v54 offset0:49 offset1:57
	ds_read2_b32 v[60:61], v54 offset0:82 offset1:90
	ds_read2_b32 v[62:63], v54 offset0:115 offset1:123
	s_waitcnt lgkmcnt(3)
	v_bfe_u32 v2, v56, 16, 1
	v_add3_u32 v2, v56, v2, s62
	s_waitcnt lgkmcnt(2)
	v_bfe_u32 v43, v58, 16, 1
	ds_read2_b32 v[64:65], v54 offset0:148 offset1:156
	v_lshrrev_b32_e32 v2, 16, v2
	v_add3_u32 v43, v58, v43, s62
	ds_read2_b32 v[66:67], v54 offset0:181 offset1:189
	v_and_or_b32 v48, v43, s33, v2
	s_waitcnt lgkmcnt(3)
	v_bfe_u32 v2, v60, 16, 1
	v_add3_u32 v2, v60, v2, s62
	s_waitcnt lgkmcnt(2)
	v_bfe_u32 v43, v62, 16, 1
	ds_read2_b32 v[68:69], v54 offset0:214 offset1:222
	v_lshrrev_b32_e32 v2, 16, v2
	v_add3_u32 v43, v62, v43, s62
	ds_read2_b32 v[70:71], v54 offset0:247 offset1:255
	v_and_or_b32 v49, v43, s33, v2
	s_waitcnt lgkmcnt(3)
	v_bfe_u32 v2, v64, 16, 1
	v_add3_u32 v2, v64, v2, s62
	s_waitcnt lgkmcnt(2)
	v_bfe_u32 v43, v66, 16, 1
	v_lshrrev_b32_e32 v2, 16, v2
	v_add3_u32 v43, v66, v43, s62
	v_and_or_b32 v50, v43, s33, v2
	s_waitcnt lgkmcnt(1)
	v_bfe_u32 v2, v68, 16, 1
	v_add3_u32 v2, v68, v2, s62
	s_waitcnt lgkmcnt(0)
	v_bfe_u32 v43, v70, 16, 1
	v_lshrrev_b32_e32 v2, 16, v2
	v_add3_u32 v43, v70, v43, s62
	v_and_or_b32 v51, v43, s33, v2
	v_bfe_u32 v2, v57, 16, 1
	v_add3_u32 v2, v57, v2, s62
	v_bfe_u32 v43, v59, 16, 1
	v_lshl_add_u64 v[72:73], v[44:45], 0, v[38:39]
	v_lshrrev_b32_e32 v2, 16, v2
	v_add3_u32 v43, v59, v43, s62
	global_store_dwordx4 v[72:73], v[48:51], off sc0 sc1
	v_lshl_add_u64 v[44:45], v[44:45], 0, v[40:41]
	s_addk_i32 s1, 0x2000
	v_and_or_b32 v48, v43, s33, v2
	v_bfe_u32 v2, v61, 16, 1
	v_add3_u32 v2, v61, v2, s62
	v_bfe_u32 v43, v63, 16, 1
	v_lshrrev_b32_e32 v2, 16, v2
	v_add3_u32 v43, v63, v43, s62
	v_and_or_b32 v49, v43, s33, v2
	v_bfe_u32 v2, v65, 16, 1
	v_add3_u32 v2, v65, v2, s62
	v_bfe_u32 v43, v67, 16, 1
	v_lshrrev_b32_e32 v2, 16, v2
	v_add3_u32 v43, v67, v43, s62
	v_and_or_b32 v50, v43, s33, v2
	v_bfe_u32 v2, v69, 16, 1
	v_add3_u32 v2, v69, v2, s62
	v_bfe_u32 v43, v71, 16, 1
	v_lshrrev_b32_e32 v2, 16, v2
	v_add3_u32 v43, v71, v43, s62
	v_and_or_b32 v51, v43, s33, v2
	global_store_dwordx4 v[44:45], v[48:51], off sc0 sc1
	s_waitcnt lgkmcnt(0)
	s_addk_i32 s12, 0x200
	s_cmpk_gt_i32 s0, 0x97f
	v_mov_b64_e32 v[44:45], v[46:47]
	s_mov_b32 s0, s13
	s_cbranch_scc1 .LBB0_951
